# L=4096 conv: K-chunk re-association for all 11 windows (peeled last window included)
# speedup vs baseline: 1.0019x; 1.0019x over previous
; #define LAS __attribute__((address_space(3)))
; #define LDS_WAIT() asm volatile("s_waitcnt lgkmcnt(0)" ::: "memory")
; #define CONV_LD(A_, B0_, B1_, m_) do { const int xA_ = xw + 16 * (m_); A_ = *(const LAS bf16x8*)(fr + 2 * xA_ + ((xA_ >> LOGRS) << 4)); \
;             B0_ = *(const LAS bf16x8*)(ubp0 + 16 * (m_)); B1_ = *(const LAS bf16x8*)(ubp1 + 16 * (m_)); } while (0)
; template <int L, int NB>
; DI void conv_unit(const Frame& F, int c, const bf16* FRg, const float* F0, const float* hyD, const bf16* UT, bf16* YT, int tok0, bool dry) {
;     ...
;     const int xA0 = L - RS * r32 + 8 * hh - RS;
;     const LAS unsigned char* ubp0 = uw + bb * BST + hh * WN + 16 * jj;
;     const LAS unsigned char* ubp1 = uw + bb * BST + (1 - hh) * WN + 16 * (jj + hh);
;     for (int win = 0; win < NWIN; ++win) {
;         asm volatile("" ::: "memory");
; #pragma unroll
;         for (int r = 0; r < 5; ++r) { const int cid = lane + 64 * r, b = cid / WCH, q = cid % WCH;
;             *(LAS u32x4*)(uw + b * BST + (q & 1) * WN + 16 * (q >> 1)) = shift8(lo[r], hi[r], wave); }
;         LDS_WAIT();
;         if (win + 1 < NWIN) CONV_ISSUE(win + 1);
;         int nst = (NSTEPS - win * WSTEPS) < WSTEPS ? (NSTEPS - win * WSTEPS) : WSTEPS;
;     ...
;         if (dry) nst = 4;
;     ...
;         const int xw = xA0 + win * WSTEPS * 16;
;     ...
;         for (int m = 0; m < nst; ++m) { bf16x8 a_, b0_, b1_; CONV_LD(a_, b0_, b1_, m);
;             acc0 = __builtin_amdgcn_mfma_f32_32x32x16_bf16(a_, b0_, acc0, 0, 0, 0);
;             acc1 = __builtin_amdgcn_mfma_f32_32x32x16_bf16(a_, b1_, acc1, 0, 0, 0); }
;     ...
;         bf16x8 fa[3][2], fb0[3][2], fb1[3][2];
;         fa[2][0] = (bf16x8){0, 0, 0, 0, 0, 0, 0, 0}; fa[2][1] = fa[2][0]; fb0[2][0] = fa[2][0]; fb0[2][1] = fa[2][0]; fb1[2][0] = fa[2][0]; fb1[2][1] = fa[2][0];
;         CONV_GLD(0, 0); CONV_GLD(1, 1);
;         const int ng = nst >> 1;
;         int g = 0;
;         for (; g + 3 < ng; g += 3) {
;             CONV_MM(0); CONV_KEEP(2); CONV_GLD(2, g + 2);
;             CONV_MM(1); CONV_KEEP(0); CONV_GLD(0, g + 3);
;             CONV_MM(2); CONV_KEEP(1); CONV_GLD(1, g + 4);
;         }
;         CONV_MM(0); CONV_KEEP(2); CONV_GLD(2, g + 2);
;         CONV_MM(1); CONV_KEEP(0);
;         CONV_MM(2); CONV_KEEP(1);
;         CONV_KEEP(2);
;     ...
;         LDS_WAIT();
.LBB0_890:
	ds_write_b128 v234, v[42:45] offset:4224
	s_waitcnt lgkmcnt(0)
	v_and_b32_e32 v243, 31, v148
	v_lshlrev_b32_e32 v243, 7, v243
	v_sub_u32_e32 v240, 0xf80, v243
	v_lshrrev_b32_e32 v243, 5, v148
	v_lshl_add_u32 v240, v243, 5, v240
	v_add_u32_e32 v240, s1, v240
	v_mul_u32_u24_e32 v243, 0x260, v243
	v_sub_u32_e32 v238, v235, v243
	v_add_u32_e32 v239, 0x280, v238
	v_ashrrev_i32_e32 v241, 3, v240
	v_and_b32_e32 v241, -16, v241
	v_lshl_add_u32 v241, v240, 1, v241
	v_add_u32_e32 v243, 64, v240
	v_ashrrev_i32_e32 v242, 3, v243
	v_and_b32_e32 v242, -16, v242
	v_lshl_add_u32 v242, v243, 1, v242
	ds_read_b128 v[76:79], v241
	ds_read_b128 v[92:95], v238
	ds_read_b128 v[80:83], v241 offset:16
	ds_read_b128 v[96:99], v239
	ds_read_b128 v[84:87], v241 offset:32
	ds_read_b128 v[100:103], v238 offset:16
	ds_read_b128 v[88:91], v241 offset:48
	ds_read_b128 v[104:107], v239 offset:16
	ds_read_b128 v[108:111], v238 offset:32
	ds_read_b128 v[112:115], v242
	ds_read_b128 v[128:131], v238 offset:64
	ds_read_b128 v[116:119], v242 offset:16
	ds_read_b128 v[132:135], v239 offset:64
	ds_read_b128 v[120:123], v242 offset:32
	ds_read_b128 v[136:139], v238 offset:80
	ds_read_b128 v[124:127], v242 offset:48
	ds_read_b128 v[140:143], v239 offset:80
	ds_read_b128 v[144:147], v238 offset:96
	v_add_u32_e32 v243, 128, v240
	v_ashrrev_i32_e32 v241, 3, v243
	v_and_b32_e32 v241, -16, v241
	v_lshl_add_u32 v241, v243, 1, v241
	v_add_u32_e32 v243, 192, v240
	v_ashrrev_i32_e32 v242, 3, v243
	v_and_b32_e32 v242, -16, v242
	v_lshl_add_u32 v242, v243, 1, v242
	s_waitcnt lgkmcnt(9)
	v_mfma_f32_32x32x16_bf16 v[2:17], v[76:79], v[92:95], v[2:17]
	v_mfma_f32_32x32x16_bf16 v[18:33], v[76:79], v[96:99], v[18:33]
	ds_read_b128 v[76:79], v241
	ds_read_b128 v[92:95], v238 offset:128
	v_mfma_f32_32x32x16_bf16 v[2:17], v[80:83], v[96:99], v[2:17]
	v_mfma_f32_32x32x16_bf16 v[18:33], v[80:83], v[100:103], v[18:33]
	ds_read_b128 v[80:83], v241 offset:16
	ds_read_b128 v[96:99], v239 offset:128
	v_mfma_f32_32x32x16_bf16 v[2:17], v[84:87], v[100:103], v[2:17]
	v_mfma_f32_32x32x16_bf16 v[18:33], v[84:87], v[104:107], v[18:33]
	ds_read_b128 v[84:87], v241 offset:32
	ds_read_b128 v[100:103], v238 offset:144
	v_mfma_f32_32x32x16_bf16 v[2:17], v[88:91], v[104:107], v[2:17]
	v_mfma_f32_32x32x16_bf16 v[18:33], v[88:91], v[108:111], v[18:33]
	ds_read_b128 v[88:91], v241 offset:48
	ds_read_b128 v[104:107], v239 offset:144
	ds_read_b128 v[108:111], v238 offset:160
	s_waitcnt lgkmcnt(9)
	v_mfma_f32_32x32x16_bf16 v[2:17], v[112:115], v[128:131], v[2:17]
	v_mfma_f32_32x32x16_bf16 v[18:33], v[112:115], v[132:135], v[18:33]
	ds_read_b128 v[112:115], v242
	ds_read_b128 v[128:131], v238 offset:192
	v_mfma_f32_32x32x16_bf16 v[2:17], v[116:119], v[132:135], v[2:17]
	v_mfma_f32_32x32x16_bf16 v[18:33], v[116:119], v[136:139], v[18:33]
	ds_read_b128 v[116:119], v242 offset:16
	ds_read_b128 v[132:135], v239 offset:192
	v_mfma_f32_32x32x16_bf16 v[2:17], v[120:123], v[136:139], v[2:17]
	v_mfma_f32_32x32x16_bf16 v[18:33], v[120:123], v[140:143], v[18:33]
	ds_read_b128 v[120:123], v242 offset:32
	ds_read_b128 v[136:139], v238 offset:208
	v_mfma_f32_32x32x16_bf16 v[2:17], v[124:127], v[140:143], v[2:17]
	v_mfma_f32_32x32x16_bf16 v[18:33], v[124:127], v[144:147], v[18:33]
	ds_read_b128 v[124:127], v242 offset:48
	ds_read_b128 v[140:143], v239 offset:208
	ds_read_b128 v[144:147], v238 offset:224
	v_add_u32_e32 v243, 256, v240
	v_ashrrev_i32_e32 v241, 3, v243
	v_and_b32_e32 v241, -16, v241
	v_lshl_add_u32 v241, v243, 1, v241
	v_add_u32_e32 v243, 320, v240
	v_ashrrev_i32_e32 v242, 3, v243
	v_and_b32_e32 v242, -16, v242
	v_lshl_add_u32 v242, v243, 1, v242
	s_waitcnt lgkmcnt(9)
	v_mfma_f32_32x32x16_bf16 v[2:17], v[76:79], v[92:95], v[2:17]
	v_mfma_f32_32x32x16_bf16 v[18:33], v[76:79], v[96:99], v[18:33]
	ds_read_b128 v[76:79], v241
	ds_read_b128 v[92:95], v238 offset:256
	v_mfma_f32_32x32x16_bf16 v[2:17], v[80:83], v[96:99], v[2:17]
	v_mfma_f32_32x32x16_bf16 v[18:33], v[80:83], v[100:103], v[18:33]
	ds_read_b128 v[80:83], v241 offset:16
	ds_read_b128 v[96:99], v239 offset:256
	v_mfma_f32_32x32x16_bf16 v[2:17], v[84:87], v[100:103], v[2:17]
	v_mfma_f32_32x32x16_bf16 v[18:33], v[84:87], v[104:107], v[18:33]
	ds_read_b128 v[84:87], v241 offset:32
	ds_read_b128 v[100:103], v238 offset:272
	v_mfma_f32_32x32x16_bf16 v[2:17], v[88:91], v[104:107], v[2:17]
	v_mfma_f32_32x32x16_bf16 v[18:33], v[88:91], v[108:111], v[18:33]
	ds_read_b128 v[88:91], v241 offset:48
	ds_read_b128 v[104:107], v239 offset:272
	ds_read_b128 v[108:111], v238 offset:288
	s_waitcnt lgkmcnt(9)
	v_mfma_f32_32x32x16_bf16 v[2:17], v[112:115], v[128:131], v[2:17]
	v_mfma_f32_32x32x16_bf16 v[18:33], v[112:115], v[132:135], v[18:33]
	ds_read_b128 v[112:115], v242
	ds_read_b128 v[128:131], v238 offset:320
	v_mfma_f32_32x32x16_bf16 v[2:17], v[116:119], v[132:135], v[2:17]
	v_mfma_f32_32x32x16_bf16 v[18:33], v[116:119], v[136:139], v[18:33]
	ds_read_b128 v[116:119], v242 offset:16
	ds_read_b128 v[132:135], v239 offset:320
	v_mfma_f32_32x32x16_bf16 v[2:17], v[120:123], v[136:139], v[2:17]
	v_mfma_f32_32x32x16_bf16 v[18:33], v[120:123], v[140:143], v[18:33]
	ds_read_b128 v[120:123], v242 offset:32
	ds_read_b128 v[136:139], v238 offset:336
	v_mfma_f32_32x32x16_bf16 v[2:17], v[124:127], v[140:143], v[2:17]
	v_mfma_f32_32x32x16_bf16 v[18:33], v[124:127], v[144:147], v[18:33]
	ds_read_b128 v[124:127], v242 offset:48
	ds_read_b128 v[140:143], v239 offset:336
	ds_read_b128 v[144:147], v238 offset:352
	s_waitcnt lgkmcnt(9)
	v_mfma_f32_32x32x16_bf16 v[2:17], v[76:79], v[92:95], v[2:17]
	v_mfma_f32_32x32x16_bf16 v[18:33], v[76:79], v[96:99], v[18:33]
	v_mfma_f32_32x32x16_bf16 v[2:17], v[80:83], v[96:99], v[2:17]
	v_mfma_f32_32x32x16_bf16 v[18:33], v[80:83], v[100:103], v[18:33]
	v_mfma_f32_32x32x16_bf16 v[2:17], v[84:87], v[100:103], v[2:17]
	v_mfma_f32_32x32x16_bf16 v[18:33], v[84:87], v[104:107], v[18:33]
	v_mfma_f32_32x32x16_bf16 v[2:17], v[88:91], v[104:107], v[2:17]
	v_mfma_f32_32x32x16_bf16 v[18:33], v[88:91], v[108:111], v[18:33]
	s_waitcnt lgkmcnt(0)
	s_barrier
; #define LAS __attribute__((address_space(3)))
; DI bf16 f2bf(float f) { return (bf16)(pk2(f, 0.f) & 0xffffu); }
; DI int crow(int reg, int h) { return (reg & 3) + 8 * (reg >> 2) + 4 * h; }
; #define CONV_KEEP(k_) asm volatile("" :: "v"(fa[k_][0]), "v"(fb0[k_][0]), "v"(fb1[k_][0]), "v"(fa[k_][1]), "v"(fb0[k_][1]), "v"(fb1[k_][1]))
; template <int L, int NB>
; DI void conv_unit(const Frame& F, int c, const bf16* FRg, const float* F0, const float* hyD, const bf16* UT, bf16* YT, int tok0, bool dry) {
;     ...
;         CONV_MM(0); CONV_KEEP(2); CONV_GLD(2, g + 2);
;         CONV_MM(1); CONV_KEEP(0);
;         CONV_MM(2); CONV_KEEP(1);
;         CONV_KEEP(2);
;     ...
;     LAS bf16* ys = (LAS bf16*)F.lds;
; #pragma unroll
;     for (int i = 0; i < 16; ++i) { const int t = RS * crow(i, hh) + 16 * jj + wave;
;         ys[bb * L + t] = f2bf(acc0[i]); ys[bb * L + t + 8] = f2bf(acc1[i]); }
	s_mov_b64 s[26:27], 0
	v_mfma_f32_32x32x16_bf16 v[2:17], v[112:115], v[128:131], v[2:17]
	v_mfma_f32_32x32x16_bf16 v[18:33], v[112:115], v[132:135], v[18:33]
	v_mfma_f32_32x32x16_bf16 v[2:17], v[116:119], v[132:135], v[2:17]
	v_mfma_f32_32x32x16_bf16 v[18:33], v[116:119], v[136:139], v[18:33]
	v_mfma_f32_32x32x16_bf16 v[2:17], v[120:123], v[136:139], v[2:17]
	v_mfma_f32_32x32x16_bf16 v[18:33], v[120:123], v[140:143], v[18:33]
	v_mfma_f32_32x32x16_bf16 v[2:17], v[124:127], v[140:143], v[2:17]
	v_mfma_f32_32x32x16_bf16 v[18:33], v[124:127], v[144:147], v[18:33]
	s_nop 0
	s_nop 0
	s_nop 0
	s_nop 0
	s_nop 10
	v_cvt_pk_bf16_f32 v1, v2, s0
	ds_write_b16 v160, v1
	v_mov_b32_e32 v2, v191
	v_cvt_pk_bf16_f32 v1, v18, s0
	ds_write_b16 v160, v1 offset:16
	v_cvt_pk_bf16_f32 v1, v3, s0
	ds_write_b16 v160, v1 offset:256
	v_cvt_pk_bf16_f32 v1, v19, s0
	ds_write_b16 v160, v1 offset:272
	v_cvt_pk_bf16_f32 v1, v4, s0
	ds_write_b16 v160, v1 offset:512
	v_cvt_pk_bf16_f32 v1, v20, s0
	ds_write_b16 v160, v1 offset:528
	v_cvt_pk_bf16_f32 v1, v5, s0
	ds_write_b16 v160, v1 offset:768
	v_cvt_pk_bf16_f32 v1, v21, s0
	ds_write_b16 v160, v1 offset:784
	v_cvt_pk_bf16_f32 v1, v6, s0
	ds_write_b16 v160, v1 offset:2048
	v_cvt_pk_bf16_f32 v1, v22, s0
	ds_write_b16 v160, v1 offset:2064
	v_cvt_pk_bf16_f32 v1, v7, s0
	ds_write_b16 v160, v1 offset:2304
	v_cvt_pk_bf16_f32 v1, v23, s0
	ds_write_b16 v160, v1 offset:2320
	v_cvt_pk_bf16_f32 v1, v8, s0
	ds_write_b16 v160, v1 offset:2560
	v_cvt_pk_bf16_f32 v1, v24, s0
	ds_write_b16 v160, v1 offset:2576
	v_cvt_pk_bf16_f32 v1, v9, s0
	ds_write_b16 v160, v1 offset:2816
	v_cvt_pk_bf16_f32 v1, v25, s0
	ds_write_b16 v160, v1 offset:2832
	v_cvt_pk_bf16_f32 v1, v10, s0
	ds_write_b16 v160, v1 offset:4096
	v_cvt_pk_bf16_f32 v1, v26, s0
	ds_write_b16 v160, v1 offset:4112
	v_cvt_pk_bf16_f32 v1, v11, s0
	ds_write_b16 v160, v1 offset:4352
	v_cvt_pk_bf16_f32 v1, v27, s0
	ds_write_b16 v160, v1 offset:4368
	v_cvt_pk_bf16_f32 v1, v12, s0
	ds_write_b16 v160, v1 offset:4608
	v_cvt_pk_bf16_f32 v1, v28, s0
	ds_write_b16 v160, v1 offset:4624
	v_cvt_pk_bf16_f32 v1, v13, s0
	ds_write_b16 v160, v1 offset:4864
	v_cvt_pk_bf16_f32 v1, v29, s0
	ds_write_b16 v160, v1 offset:4880
	v_cvt_pk_bf16_f32 v1, v14, s0
	ds_write_b16 v160, v1 offset:6144
	v_cvt_pk_bf16_f32 v1, v30, s0
	ds_write_b16 v160, v1 offset:6160
	v_cvt_pk_bf16_f32 v1, v15, s0
	ds_write_b16 v160, v1 offset:6400
	v_cvt_pk_bf16_f32 v1, v31, s0
	ds_write_b16 v160, v1 offset:6416
	v_cvt_pk_bf16_f32 v1, v16, s0
	ds_write_b16 v160, v1 offset:6656
	v_cvt_pk_bf16_f32 v1, v32, s0
	ds_write_b16 v160, v1 offset:6672
	v_cvt_pk_bf16_f32 v1, v17, s0
	ds_write_b16 v160, v1 offset:6912
	v_cvt_pk_bf16_f32 v1, v33, s0
	ds_write_b16 v160, v1 offset:6928
	v_mov_b32_e32 v1, v168
	v_mov_b32_e32 v3, v169
	s_waitcnt lgkmcnt(0)
	s_barrier
